# v35 barrier (write-back, release, then acquire) plus the start-phase grid sync routed through the same XCD barrier
# baseline (speedup 1.0000x reference)
.LBB0_517:
	s_cmp_lt_i32 s24, 2
	s_cselect_b64 s[0:1], -1, 0
	s_xor_b64 s[6:7], s[6:7], -1
	s_or_b64 s[0:1], s[0:1], s[6:7]
	s_and_b64 vcc, exec, s[0:1]
	s_cbranch_vccnz .LBB0_5
	s_cmp_lg_u32 s24, 2
	s_mov_b64 s[6:7], -1
	s_waitcnt vmcnt(0) lgkmcnt(0)
	v_readlane_b32 s28, v254, 41
	v_readlane_b32 s29, v254, 42
	v_readlane_b32 s0, v254, 28
	s_load_dwordx2 s[28:29], s[28:29], 0x120
	s_add_i32 s13, s0, 1
	s_waitcnt vmcnt(0)
	s_barrier
	s_mov_b64 s[6:7], exec
	v_readlane_b32 s0, v254, 29
	v_readlane_b32 s1, v254, 30
	s_and_b64 s[0:1], s[6:7], s[0:1]
	s_mov_b64 exec, s[0:1]
	s_cbranch_execz .LBB0_525
	s_getreg_b32 s8, hwreg(HW_REG_XCC_ID, 0, 4)
	s_and_b32 s8, s8, 7
	s_lshr_b32 s9, s54, 3
	v_mov_b32_e32 v1, 1
	s_mul_i32 s9, s9, s13
	s_lshl_b32 s11, s8, 4
	s_lshl_b32 s18, s8, 3
	s_add_u32 s18, s18, 0x80
	v_mov_b32_e32 v3, s11
	v_mov_b32_e32 v5, s18
	s_waitcnt lgkmcnt(0)
	s_add_u32 s0, s28, 0x198000
	s_addc_u32 s1, s29, 0
	global_atomic_add v3, v3, v1, s[0:1] sc0
	s_mov_b32 s20, 0
	s_lshl_b32 s21, s13, 3
	s_waitcnt vmcnt(0)
	v_add_u32_e32 v3, 1, v3
	v_cmp_eq_u32_e32 vcc, s9, v3
	s_cbranch_vccz .Lxb_early
	buffer_wbl2 sc1
	s_waitcnt vmcnt(0)
	global_atomic_add v3, v2, v1, s[0:1] offset:192 sc0
	s_waitcnt vmcnt(0)
	v_add_u32_e32 v3, 1, v3
	v_cmp_eq_u32_e32 vcc, s21, v3
	s_cbranch_vccz .Lxb_fspin
	global_atomic_add v2, v1, s[0:1] offset:128
	global_atomic_add v2, v1, s[0:1] offset:136
	global_atomic_add v2, v1, s[0:1] offset:144
	global_atomic_add v2, v1, s[0:1] offset:152
	global_atomic_add v2, v1, s[0:1] offset:160
	global_atomic_add v2, v1, s[0:1] offset:168
	global_atomic_add v2, v1, s[0:1] offset:176
	global_atomic_add v2, v1, s[0:1] offset:184
	s_branch .Lxb_facq
